# dn epilogue: residual-stream (XB) tile stores issued with the nt policy (test), on top of v59
# speedup vs baseline: 1.0056x; 1.0056x over previous
; __device__ __forceinline__ u32x4 pack8(const f32x4& a, const f32x4& b) { u32x4 w; w.x = cvt_pk_bf16(a[0], a[1]); w.y = cvt_pk_bf16(a[2], a[3]); w.z = cvt_pk_bf16(b[0], b[1]); w.w = cvt_pk_bf16(b[2], b[3]); return w; }
;     __device__ __forceinline__ void operator()(const f32x4 (&acc)[2][2][4][2], const Unit& u, int ui, int wr, int wc, int fr, int fq) const {
;     ...
;             for (int m = 0; m < 4; ++m) { const int row = row0 + ai * HALF + m * 16; const size_t off = (size_t)row * 1024 + col0; float q = 0.f;
;                 f32x4 v[2][2];
;                 if (basef) {
; #pragma unroll
;                     for (int bj = 0; bj < 2; ++bj) { v[bj][0] = *(const f32x4*)(basef + off + bj * HALF); v[bj][1] = *(const f32x4*)(basef + off + bj * HALF + 4); }
;                 } else {
; #pragma unroll
;                     for (int bj = 0; bj < 2; ++bj) { const u32x4 raw = *(const u32x4*)(xb + off + bj * HALF);
;                         v[bj][0] = (f32x4){__builtin_bit_cast(float, raw.x << 16), __builtin_bit_cast(float, raw.x & 0xffff0000u), __builtin_bit_cast(float, raw.y << 16), __builtin_bit_cast(float, raw.y & 0xffff0000u)};
;                         v[bj][1] = (f32x4){__builtin_bit_cast(float, raw.z << 16), __builtin_bit_cast(float, raw.z & 0xffff0000u), __builtin_bit_cast(float, raw.w << 16), __builtin_bit_cast(float, raw.w & 0xffff0000u)}; }
;                 }
; #pragma unroll
;                 for (int bj = 0; bj < 2; ++bj) {
;                     f32x4 v0 = v[bj][0] + acc[ai][bj][m][0] * alpha, v1 = v[bj][1] + acc[ai][bj][m][1] * alpha;
;                     if (HAS_BIAS) { v0 += bv[bj][0]; v1 += bv[bj][1]; }
;                     if (outf) { *(f32x4*)(outf + off + bj * HALF) = v0; *(f32x4*)(outf + off + bj * HALF + 4) = v1; }
;                     else *(u32x4*)(xb + off + bj * HALF) = pack8(v0, v1);
;                     q += (v0[0] * v0[0] + v0[1] * v0[1]) + (v0[2] * v0[2] + v0[3] * v0[3]) + (v1[0] * v1[0] + v1[1] * v1[1]) + (v1[2] * v1[2] + v1[3] * v1[3]); }
;                 q += __shfl_xor(q, 16); q += __shfl_xor(q, 32);
;                 if (fq == 0) ssp[(size_t)row * 16 + u.pn * 4 + wc] = q;
.LBB0_551:
	s_waitcnt vmcnt(0)
	v_pk_fma_f32 v[124:125], v[124:125], 0.5, v[140:141] op_sel_hi:[1,0,1]
	v_pk_fma_f32 v[126:127], v[126:127], 0.5, v[142:143] op_sel_hi:[1,0,1]
	v_pk_fma_f32 v[138:139], v[122:123], 0.5, v[138:139] op_sel_hi:[1,0,1]
	v_pk_fma_f32 v[122:123], v[120:121], 0.5, v[136:137] op_sel_hi:[1,0,1]
	v_cvt_pk_bf16_f32 v120, v124, v125
	v_mul_f32_e32 v124, v124, v124
	v_fmac_f32_e32 v124, v125, v125
	v_mul_f32_e32 v125, v126, v126
	v_fmac_f32_e32 v125, v127, v127
	v_add_f32_e32 v124, v125, v124
	v_mul_f32_e32 v125, v122, v122
	v_pk_fma_f32 v[118:119], v[118:119], 0.5, v[134:135] op_sel_hi:[1,0,1]
	v_pk_fma_f32 v[116:117], v[116:117], 0.5, v[132:133] op_sel_hi:[1,0,1]
	v_cvt_pk_bf16_f32 v121, v126, v127
	v_fmac_f32_e32 v125, v123, v123
	v_pk_fma_f32 v[126:127], v[112:113], 0.5, v[128:129] op_sel_hi:[1,0,1]
	v_mul_f32_e32 v112, v116, v116
	v_mul_f32_e32 v113, v118, v118
	v_add_f32_e32 v124, v125, v124
	v_mul_f32_e32 v125, v139, v139
	v_fmac_f32_e32 v112, v117, v117
	v_fmac_f32_e32 v113, v119, v119
	v_fmac_f32_e32 v125, v138, v138
	v_add_f32_e32 v112, v113, v112
	v_mul_f32_e32 v113, v126, v126
	v_add_f32_e32 v136, v125, v124
	v_pk_fma_f32 v[124:125], v[114:115], 0.5, v[130:131] op_sel_hi:[1,0,1]
	v_fmac_f32_e32 v113, v127, v127
	v_add_f32_e32 v112, v113, v112
	v_mul_f32_e32 v113, v124, v124
	v_fmac_f32_e32 v113, v125, v125
	v_and_b32_e32 v114, 64, v192
	v_add_f32_e32 v112, v113, v112
	v_xor_b32_e32 v113, 16, v192
	v_add_u32_e32 v115, 64, v114
	v_cmp_lt_i32_e32 vcc, v113, v115
	v_add_f32_e32 v112, v136, v112
	s_lshl_b32 s0, s56, 2
	v_cndmask_b32_e32 v113, v192, v113, vcc
	v_lshlrev_b32_e32 v132, 2, v113
	ds_bpermute_b32 v113, v132, v112
	v_cmp_eq_u32_e64 s[10:11], 0, v183
	s_ashr_i32 s1, s0, 31
	v_cvt_pk_bf16_f32 v122, v122, v123
	v_cvt_pk_bf16_f32 v123, v138, v139
	s_waitcnt lgkmcnt(0)
	v_add_f32_e32 v112, v112, v113
	v_xor_b32_e32 v113, 32, v192
	v_cmp_lt_i32_e32 vcc, v113, v115
	global_store_dwordx4 v[178:179], v[120:123], off nt
	v_cvt_pk_bf16_f32 v114, v116, v117
	v_cvt_pk_bf16_f32 v115, v118, v119
	v_cvt_pk_bf16_f32 v116, v126, v127
	v_cvt_pk_bf16_f32 v117, v124, v125
	s_nop 0
	v_cndmask_b32_e32 v113, v192, v113, vcc
	v_lshlrev_b32_e32 v133, 2, v113
	ds_bpermute_b32 v113, v133, v112
	global_store_dwordx4 v[178:179], v[114:117], off offset:256 nt
	s_and_saveexec_b64 s[2:3], s[10:11]
	s_cbranch_execz .LBB0_553
	v_lshlrev_b64 v[114:115], 6, v[176:177]
	v_lshl_add_u64 v[114:115], s[20:21], 0, v[114:115]
	v_lshl_add_u64 v[114:115], s[0:1], 2, v[114:115]
	s_lshl_b32 s88, s44, 2
	v_lshl_add_u64 v[114:115], v[114:115], 0, s[88:89]
	s_waitcnt lgkmcnt(0)
	v_add_f32_e32 v112, v112, v113
	global_store_dword v[114:115], v112, off

; __device__ __forceinline__ u32x4 pack8(const f32x4& a, const f32x4& b) { u32x4 w; w.x = cvt_pk_bf16(a[0], a[1]); w.y = cvt_pk_bf16(a[2], a[3]); w.z = cvt_pk_bf16(b[0], b[1]); w.w = cvt_pk_bf16(b[2], b[3]); return w; }
;     __device__ __forceinline__ void operator()(const f32x4 (&acc)[2][2][4][2], const Unit& u, int ui, int wr, int wc, int fr, int fq) const {
;     ...
;             for (int m = 0; m < 4; ++m) { const int row = row0 + ai * HALF + m * 16; const size_t off = (size_t)row * 1024 + col0; float q = 0.f;
;                 f32x4 v[2][2];
;                 if (basef) {
; #pragma unroll
;                     for (int bj = 0; bj < 2; ++bj) { v[bj][0] = *(const f32x4*)(basef + off + bj * HALF); v[bj][1] = *(const f32x4*)(basef + off + bj * HALF + 4); }
;                 } else {
; #pragma unroll
;                     for (int bj = 0; bj < 2; ++bj) { const u32x4 raw = *(const u32x4*)(xb + off + bj * HALF);
;                         v[bj][0] = (f32x4){__builtin_bit_cast(float, raw.x << 16), __builtin_bit_cast(float, raw.x & 0xffff0000u), __builtin_bit_cast(float, raw.y << 16), __builtin_bit_cast(float, raw.y & 0xffff0000u)};
;                         v[bj][1] = (f32x4){__builtin_bit_cast(float, raw.z << 16), __builtin_bit_cast(float, raw.z & 0xffff0000u), __builtin_bit_cast(float, raw.w << 16), __builtin_bit_cast(float, raw.w & 0xffff0000u)}; }
;                 }
; #pragma unroll
;                 for (int bj = 0; bj < 2; ++bj) {
;                     f32x4 v0 = v[bj][0] + acc[ai][bj][m][0] * alpha, v1 = v[bj][1] + acc[ai][bj][m][1] * alpha;
;                     if (HAS_BIAS) { v0 += bv[bj][0]; v1 += bv[bj][1]; }
;                     if (outf) { *(f32x4*)(outf + off + bj * HALF) = v0; *(f32x4*)(outf + off + bj * HALF + 4) = v1; }
;                     else *(u32x4*)(xb + off + bj * HALF) = pack8(v0, v1);
;                     q += (v0[0] * v0[0] + v0[1] * v0[1]) + (v0[2] * v0[2] + v0[3] * v0[3]) + (v1[0] * v1[0] + v1[1] * v1[1]) + (v1[2] * v1[2] + v1[3] * v1[3]); }
;                 q += __shfl_xor(q, 16); q += __shfl_xor(q, 32);
;                 if (fq == 0) ssp[(size_t)row * 16 + u.pn * 4 + wc] = q;
.LBB0_556:
	s_waitcnt vmcnt(3)
	v_pk_fma_f32 v[108:109], v[108:109], 0.5, v[124:125] op_sel_hi:[1,0,1]
	v_pk_fma_f32 v[110:111], v[110:111], 0.5, v[126:127] op_sel_hi:[1,0,1]
	s_waitcnt vmcnt(2)
	v_pk_fma_f32 v[122:123], v[106:107], 0.5, v[122:123] op_sel_hi:[1,0,1]
	v_pk_fma_f32 v[106:107], v[104:105], 0.5, v[120:121] op_sel_hi:[1,0,1]
	v_cvt_pk_bf16_f32 v104, v108, v109
	v_mul_f32_e32 v108, v108, v108
	v_fmac_f32_e32 v108, v109, v109
	v_mul_f32_e32 v109, v110, v110
	v_fmac_f32_e32 v109, v111, v111
	v_add_f32_e32 v108, v109, v108
	v_mul_f32_e32 v109, v106, v106
	s_waitcnt vmcnt(1)
	v_pk_fma_f32 v[102:103], v[102:103], 0.5, v[118:119] op_sel_hi:[1,0,1]
	v_pk_fma_f32 v[100:101], v[100:101], 0.5, v[116:117] op_sel_hi:[1,0,1]
	v_cvt_pk_bf16_f32 v105, v110, v111
	v_fmac_f32_e32 v109, v107, v107
	s_waitcnt vmcnt(0)
	v_pk_fma_f32 v[110:111], v[96:97], 0.5, v[112:113] op_sel_hi:[1,0,1]
	v_mul_f32_e32 v96, v100, v100
	v_mul_f32_e32 v97, v102, v102
	v_add_f32_e32 v108, v109, v108
	v_mul_f32_e32 v109, v123, v123
	v_fmac_f32_e32 v96, v101, v101
	v_fmac_f32_e32 v97, v103, v103
	v_fmac_f32_e32 v109, v122, v122
	v_add_f32_e32 v96, v97, v96
	v_mul_f32_e32 v97, v110, v110
	v_add_f32_e32 v120, v109, v108
	v_pk_fma_f32 v[108:109], v[98:99], 0.5, v[114:115] op_sel_hi:[1,0,1]
	v_fmac_f32_e32 v97, v111, v111
	v_add_f32_e32 v96, v97, v96
	v_mul_f32_e32 v97, v108, v108
	v_fmac_f32_e32 v97, v109, v109
	v_add_f32_e32 v96, v97, v96
	v_add_f32_e32 v96, v120, v96
	ds_bpermute_b32 v97, v132, v96
	v_cvt_pk_bf16_f32 v106, v106, v107
	v_cvt_pk_bf16_f32 v107, v122, v123
	global_store_dwordx4 v[130:131], v[104:107], off nt
	v_cvt_pk_bf16_f32 v98, v100, v101
	s_waitcnt lgkmcnt(0)
	v_add_f32_e32 v96, v96, v97
	ds_bpermute_b32 v97, v133, v96
	v_cvt_pk_bf16_f32 v99, v102, v103
	v_cvt_pk_bf16_f32 v100, v110, v111
	v_cvt_pk_bf16_f32 v101, v108, v109
	global_store_dwordx4 v[130:131], v[98:101], off offset:256 nt
	s_and_saveexec_b64 s[2:3], s[10:11]
	s_cbranch_execz .LBB0_558
	v_lshlrev_b64 v[98:99], 6, v[128:129]
	v_lshl_add_u64 v[98:99], s[20:21], 0, v[98:99]
	v_lshl_add_u64 v[98:99], s[0:1], 2, v[98:99]
	s_lshl_b32 s88, s44, 2
	v_lshl_add_u64 v[98:99], v[98:99], 0, s[88:89]
	s_waitcnt lgkmcnt(0)
	v_add_f32_e32 v96, v96, v97
	global_store_dword v[98:99], v96, off

; __device__ __forceinline__ u32x4 pack8(const f32x4& a, const f32x4& b) { u32x4 w; w.x = cvt_pk_bf16(a[0], a[1]); w.y = cvt_pk_bf16(a[2], a[3]); w.z = cvt_pk_bf16(b[0], b[1]); w.w = cvt_pk_bf16(b[2], b[3]); return w; }
;     __device__ __forceinline__ void operator()(const f32x4 (&acc)[2][2][4][2], const Unit& u, int ui, int wr, int wc, int fr, int fq) const {
;     ...
;             for (int m = 0; m < 4; ++m) { const int row = row0 + ai * HALF + m * 16; const size_t off = (size_t)row * 1024 + col0; float q = 0.f;
;                 f32x4 v[2][2];
;                 if (basef) {
; #pragma unroll
;                     for (int bj = 0; bj < 2; ++bj) { v[bj][0] = *(const f32x4*)(basef + off + bj * HALF); v[bj][1] = *(const f32x4*)(basef + off + bj * HALF + 4); }
;                 } else {
; #pragma unroll
;                     for (int bj = 0; bj < 2; ++bj) { const u32x4 raw = *(const u32x4*)(xb + off + bj * HALF);
;                         v[bj][0] = (f32x4){__builtin_bit_cast(float, raw.x << 16), __builtin_bit_cast(float, raw.x & 0xffff0000u), __builtin_bit_cast(float, raw.y << 16), __builtin_bit_cast(float, raw.y & 0xffff0000u)};
;                         v[bj][1] = (f32x4){__builtin_bit_cast(float, raw.z << 16), __builtin_bit_cast(float, raw.z & 0xffff0000u), __builtin_bit_cast(float, raw.w << 16), __builtin_bit_cast(float, raw.w & 0xffff0000u)}; }
;                 }
; #pragma unroll
;                 for (int bj = 0; bj < 2; ++bj) {
;                     f32x4 v0 = v[bj][0] + acc[ai][bj][m][0] * alpha, v1 = v[bj][1] + acc[ai][bj][m][1] * alpha;
;                     if (HAS_BIAS) { v0 += bv[bj][0]; v1 += bv[bj][1]; }
;                     if (outf) { *(f32x4*)(outf + off + bj * HALF) = v0; *(f32x4*)(outf + off + bj * HALF + 4) = v1; }
;                     else *(u32x4*)(xb + off + bj * HALF) = pack8(v0, v1);
;                     q += (v0[0] * v0[0] + v0[1] * v0[1]) + (v0[2] * v0[2] + v0[3] * v0[3]) + (v1[0] * v1[0] + v1[1] * v1[1]) + (v1[2] * v1[2] + v1[3] * v1[3]); }
;                 q += __shfl_xor(q, 16); q += __shfl_xor(q, 32);
;                 if (fq == 0) ssp[(size_t)row * 16 + u.pn * 4 + wc] = q;
.LBB0_561:
	s_waitcnt vmcnt(3)
	v_pk_fma_f32 v[92:93], v[92:93], 0.5, v[108:109] op_sel_hi:[1,0,1]
	v_pk_fma_f32 v[94:95], v[94:95], 0.5, v[110:111] op_sel_hi:[1,0,1]
	s_waitcnt vmcnt(2)
	v_pk_fma_f32 v[106:107], v[90:91], 0.5, v[106:107] op_sel_hi:[1,0,1]
	v_pk_fma_f32 v[90:91], v[88:89], 0.5, v[104:105] op_sel_hi:[1,0,1]
	v_cvt_pk_bf16_f32 v88, v92, v93
	v_mul_f32_e32 v92, v92, v92
	v_fmac_f32_e32 v92, v93, v93
	v_mul_f32_e32 v93, v94, v94
	v_fmac_f32_e32 v93, v95, v95
	v_add_f32_e32 v92, v93, v92
	v_mul_f32_e32 v93, v90, v90
	s_waitcnt vmcnt(1)
	v_pk_fma_f32 v[86:87], v[86:87], 0.5, v[102:103] op_sel_hi:[1,0,1]
	v_pk_fma_f32 v[84:85], v[84:85], 0.5, v[100:101] op_sel_hi:[1,0,1]
	v_cvt_pk_bf16_f32 v89, v94, v95
	v_fmac_f32_e32 v93, v91, v91
	s_waitcnt vmcnt(0)
	v_pk_fma_f32 v[94:95], v[80:81], 0.5, v[96:97] op_sel_hi:[1,0,1]
	v_mul_f32_e32 v80, v84, v84
	v_mul_f32_e32 v81, v86, v86
	v_add_f32_e32 v92, v93, v92
	v_mul_f32_e32 v93, v107, v107
	v_fmac_f32_e32 v80, v85, v85
	v_fmac_f32_e32 v81, v87, v87
	v_fmac_f32_e32 v93, v106, v106
	v_add_f32_e32 v80, v81, v80
	v_mul_f32_e32 v81, v94, v94
	v_add_f32_e32 v104, v93, v92
	v_pk_fma_f32 v[92:93], v[82:83], 0.5, v[98:99] op_sel_hi:[1,0,1]
	v_fmac_f32_e32 v81, v95, v95
	v_add_f32_e32 v80, v81, v80
	v_mul_f32_e32 v81, v92, v92
	v_fmac_f32_e32 v81, v93, v93
	v_add_f32_e32 v80, v81, v80
	v_add_f32_e32 v80, v104, v80
	ds_bpermute_b32 v81, v132, v80
	v_cvt_pk_bf16_f32 v90, v90, v91
	v_cvt_pk_bf16_f32 v91, v106, v107
	global_store_dwordx4 v[114:115], v[88:91], off nt
	v_cvt_pk_bf16_f32 v82, v84, v85
	s_waitcnt lgkmcnt(0)
	v_add_f32_e32 v80, v80, v81
	ds_bpermute_b32 v81, v133, v80
	v_cvt_pk_bf16_f32 v83, v86, v87
	v_cvt_pk_bf16_f32 v84, v94, v95
	v_cvt_pk_bf16_f32 v85, v92, v93
	global_store_dwordx4 v[114:115], v[82:85], off offset:256 nt
	s_and_saveexec_b64 s[2:3], s[10:11]
	s_cbranch_execz .LBB0_563
	v_lshlrev_b64 v[82:83], 6, v[112:113]
	v_lshl_add_u64 v[82:83], s[20:21], 0, v[82:83]
	v_lshl_add_u64 v[82:83], s[0:1], 2, v[82:83]
	s_lshl_b32 s88, s44, 2
	v_lshl_add_u64 v[82:83], v[82:83], 0, s[88:89]
	s_waitcnt lgkmcnt(0)
	v_add_f32_e32 v80, v80, v81
	global_store_dword v[82:83], v80, off

; __device__ __forceinline__ u32x4 pack8(const f32x4& a, const f32x4& b) { u32x4 w; w.x = cvt_pk_bf16(a[0], a[1]); w.y = cvt_pk_bf16(a[2], a[3]); w.z = cvt_pk_bf16(b[0], b[1]); w.w = cvt_pk_bf16(b[2], b[3]); return w; }
;     __device__ __forceinline__ void operator()(const f32x4 (&acc)[2][2][4][2], const Unit& u, int ui, int wr, int wc, int fr, int fq) const {
;     ...
;             for (int m = 0; m < 4; ++m) { const int row = row0 + ai * HALF + m * 16; const size_t off = (size_t)row * 1024 + col0; float q = 0.f;
;                 f32x4 v[2][2];
;                 if (basef) {
; #pragma unroll
;                     for (int bj = 0; bj < 2; ++bj) { v[bj][0] = *(const f32x4*)(basef + off + bj * HALF); v[bj][1] = *(const f32x4*)(basef + off + bj * HALF + 4); }
;                 } else {
; #pragma unroll
;                     for (int bj = 0; bj < 2; ++bj) { const u32x4 raw = *(const u32x4*)(xb + off + bj * HALF);
;                         v[bj][0] = (f32x4){__builtin_bit_cast(float, raw.x << 16), __builtin_bit_cast(float, raw.x & 0xffff0000u), __builtin_bit_cast(float, raw.y << 16), __builtin_bit_cast(float, raw.y & 0xffff0000u)};
;                         v[bj][1] = (f32x4){__builtin_bit_cast(float, raw.z << 16), __builtin_bit_cast(float, raw.z & 0xffff0000u), __builtin_bit_cast(float, raw.w << 16), __builtin_bit_cast(float, raw.w & 0xffff0000u)}; }
;                 }
; #pragma unroll
;                 for (int bj = 0; bj < 2; ++bj) {
;                     f32x4 v0 = v[bj][0] + acc[ai][bj][m][0] * alpha, v1 = v[bj][1] + acc[ai][bj][m][1] * alpha;
;                     if (HAS_BIAS) { v0 += bv[bj][0]; v1 += bv[bj][1]; }
;                     if (outf) { *(f32x4*)(outf + off + bj * HALF) = v0; *(f32x4*)(outf + off + bj * HALF + 4) = v1; }
;                     else *(u32x4*)(xb + off + bj * HALF) = pack8(v0, v1);
;                     q += (v0[0] * v0[0] + v0[1] * v0[1]) + (v0[2] * v0[2] + v0[3] * v0[3]) + (v1[0] * v1[0] + v1[1] * v1[1]) + (v1[2] * v1[2] + v1[3] * v1[3]); }
;                 q += __shfl_xor(q, 16); q += __shfl_xor(q, 32);
;                 if (fq == 0) ssp[(size_t)row * 16 + u.pn * 4 + wc] = q;
.LBB0_566:
	s_waitcnt vmcnt(3)
	v_pk_fma_f32 v[76:77], v[76:77], 0.5, v[92:93] op_sel_hi:[1,0,1]
	v_pk_fma_f32 v[78:79], v[78:79], 0.5, v[94:95] op_sel_hi:[1,0,1]
	s_waitcnt vmcnt(2)
	v_pk_fma_f32 v[90:91], v[74:75], 0.5, v[90:91] op_sel_hi:[1,0,1]
	v_pk_fma_f32 v[74:75], v[72:73], 0.5, v[88:89] op_sel_hi:[1,0,1]
	v_cvt_pk_bf16_f32 v72, v76, v77
	v_mul_f32_e32 v76, v76, v76
	v_fmac_f32_e32 v76, v77, v77
	v_mul_f32_e32 v77, v78, v78
	v_fmac_f32_e32 v77, v79, v79
	v_add_f32_e32 v76, v77, v76
	v_mul_f32_e32 v77, v74, v74
	s_waitcnt vmcnt(1)
	v_pk_fma_f32 v[70:71], v[70:71], 0.5, v[86:87] op_sel_hi:[1,0,1]
	v_pk_fma_f32 v[68:69], v[68:69], 0.5, v[84:85] op_sel_hi:[1,0,1]
	v_cvt_pk_bf16_f32 v73, v78, v79
	v_fmac_f32_e32 v77, v75, v75
	s_waitcnt vmcnt(0)
	v_pk_fma_f32 v[78:79], v[64:65], 0.5, v[80:81] op_sel_hi:[1,0,1]
	v_mul_f32_e32 v64, v68, v68
	v_mul_f32_e32 v65, v70, v70
	v_add_f32_e32 v76, v77, v76
	v_mul_f32_e32 v77, v91, v91
	v_fmac_f32_e32 v64, v69, v69
	v_fmac_f32_e32 v65, v71, v71
	v_fmac_f32_e32 v77, v90, v90
	v_add_f32_e32 v64, v65, v64
	v_mul_f32_e32 v65, v78, v78
	v_add_f32_e32 v88, v77, v76
	v_pk_fma_f32 v[76:77], v[66:67], 0.5, v[82:83] op_sel_hi:[1,0,1]
	v_fmac_f32_e32 v65, v79, v79
	v_add_f32_e32 v64, v65, v64
	v_mul_f32_e32 v65, v76, v76
	v_fmac_f32_e32 v65, v77, v77
	v_add_f32_e32 v64, v65, v64
	v_add_f32_e32 v64, v88, v64
	ds_bpermute_b32 v65, v132, v64
	v_cvt_pk_bf16_f32 v74, v74, v75
	v_cvt_pk_bf16_f32 v75, v90, v91
	global_store_dwordx4 v[98:99], v[72:75], off nt
	v_cvt_pk_bf16_f32 v66, v68, v69
	s_waitcnt lgkmcnt(0)
	v_add_f32_e32 v64, v64, v65
	ds_bpermute_b32 v65, v133, v64
	v_cvt_pk_bf16_f32 v67, v70, v71
	v_cvt_pk_bf16_f32 v68, v78, v79
	v_cvt_pk_bf16_f32 v69, v76, v77
	global_store_dwordx4 v[98:99], v[66:69], off offset:256 nt
	s_and_saveexec_b64 s[2:3], s[10:11]
	s_cbranch_execz .LBB0_568
	v_lshlrev_b64 v[66:67], 6, v[96:97]
	v_lshl_add_u64 v[66:67], s[20:21], 0, v[66:67]
	v_lshl_add_u64 v[66:67], s[0:1], 2, v[66:67]
	s_lshl_b32 s88, s44, 2
	v_lshl_add_u64 v[66:67], v[66:67], 0, s[88:89]
	s_waitcnt lgkmcnt(0)
	v_add_f32_e32 v64, v64, v65
	global_store_dword v[66:67], v64, off

; __device__ __forceinline__ u32x4 pack8(const f32x4& a, const f32x4& b) { u32x4 w; w.x = cvt_pk_bf16(a[0], a[1]); w.y = cvt_pk_bf16(a[2], a[3]); w.z = cvt_pk_bf16(b[0], b[1]); w.w = cvt_pk_bf16(b[2], b[3]); return w; }
;     __device__ __forceinline__ void operator()(const f32x4 (&acc)[2][2][4][2], const Unit& u, int ui, int wr, int wc, int fr, int fq) const {
;     ...
;             for (int m = 0; m < 4; ++m) { const int row = row0 + ai * HALF + m * 16; const size_t off = (size_t)row * 1024 + col0; float q = 0.f;
;                 f32x4 v[2][2];
;                 if (basef) {
; #pragma unroll
;                     for (int bj = 0; bj < 2; ++bj) { v[bj][0] = *(const f32x4*)(basef + off + bj * HALF); v[bj][1] = *(const f32x4*)(basef + off + bj * HALF + 4); }
;                 } else {
; #pragma unroll
;                     for (int bj = 0; bj < 2; ++bj) { const u32x4 raw = *(const u32x4*)(xb + off + bj * HALF);
;                         v[bj][0] = (f32x4){__builtin_bit_cast(float, raw.x << 16), __builtin_bit_cast(float, raw.x & 0xffff0000u), __builtin_bit_cast(float, raw.y << 16), __builtin_bit_cast(float, raw.y & 0xffff0000u)};
;                         v[bj][1] = (f32x4){__builtin_bit_cast(float, raw.z << 16), __builtin_bit_cast(float, raw.z & 0xffff0000u), __builtin_bit_cast(float, raw.w << 16), __builtin_bit_cast(float, raw.w & 0xffff0000u)}; }
;                 }
; #pragma unroll
;                 for (int bj = 0; bj < 2; ++bj) {
;                     f32x4 v0 = v[bj][0] + acc[ai][bj][m][0] * alpha, v1 = v[bj][1] + acc[ai][bj][m][1] * alpha;
;                     if (HAS_BIAS) { v0 += bv[bj][0]; v1 += bv[bj][1]; }
;                     if (outf) { *(f32x4*)(outf + off + bj * HALF) = v0; *(f32x4*)(outf + off + bj * HALF + 4) = v1; }
;                     else *(u32x4*)(xb + off + bj * HALF) = pack8(v0, v1);
;                     q += (v0[0] * v0[0] + v0[1] * v0[1]) + (v0[2] * v0[2] + v0[3] * v0[3]) + (v1[0] * v1[0] + v1[1] * v1[1]) + (v1[2] * v1[2] + v1[3] * v1[3]); }
;                 q += __shfl_xor(q, 16); q += __shfl_xor(q, 32);
;                 if (fq == 0) ssp[(size_t)row * 16 + u.pn * 4 + wc] = q;
.LBB0_571:
	s_waitcnt vmcnt(3)
	v_pk_fma_f32 v[60:61], v[60:61], 0.5, v[76:77] op_sel_hi:[1,0,1]
	v_pk_fma_f32 v[62:63], v[62:63], 0.5, v[78:79] op_sel_hi:[1,0,1]
	s_waitcnt vmcnt(2)
	v_pk_fma_f32 v[74:75], v[58:59], 0.5, v[74:75] op_sel_hi:[1,0,1]
	v_pk_fma_f32 v[58:59], v[56:57], 0.5, v[72:73] op_sel_hi:[1,0,1]
	v_cvt_pk_bf16_f32 v56, v60, v61
	v_mul_f32_e32 v60, v60, v60
	v_fmac_f32_e32 v60, v61, v61
	v_mul_f32_e32 v61, v62, v62
	v_fmac_f32_e32 v61, v63, v63
	v_add_f32_e32 v60, v61, v60
	v_mul_f32_e32 v61, v58, v58
	s_waitcnt vmcnt(1)
	v_pk_fma_f32 v[54:55], v[54:55], 0.5, v[70:71] op_sel_hi:[1,0,1]
	v_pk_fma_f32 v[52:53], v[52:53], 0.5, v[68:69] op_sel_hi:[1,0,1]
	v_cvt_pk_bf16_f32 v57, v62, v63
	v_fmac_f32_e32 v61, v59, v59
	s_waitcnt vmcnt(0)
	v_pk_fma_f32 v[62:63], v[48:49], 0.5, v[64:65] op_sel_hi:[1,0,1]
	v_mul_f32_e32 v48, v52, v52
	v_mul_f32_e32 v49, v54, v54
	v_add_f32_e32 v60, v61, v60
	v_mul_f32_e32 v61, v75, v75
	v_fmac_f32_e32 v48, v53, v53
	v_fmac_f32_e32 v49, v55, v55
	v_fmac_f32_e32 v61, v74, v74
	v_add_f32_e32 v48, v49, v48
	v_mul_f32_e32 v49, v62, v62
	v_add_f32_e32 v72, v61, v60
	v_pk_fma_f32 v[60:61], v[50:51], 0.5, v[66:67] op_sel_hi:[1,0,1]
	v_fmac_f32_e32 v49, v63, v63
	v_add_f32_e32 v48, v49, v48
	v_mul_f32_e32 v49, v60, v60
	v_fmac_f32_e32 v49, v61, v61
	v_add_f32_e32 v48, v49, v48
	v_add_f32_e32 v48, v72, v48
	ds_bpermute_b32 v49, v132, v48
	v_cvt_pk_bf16_f32 v58, v58, v59
	v_cvt_pk_bf16_f32 v59, v74, v75
	global_store_dwordx4 v[82:83], v[56:59], off nt
	v_cvt_pk_bf16_f32 v50, v52, v53
	s_waitcnt lgkmcnt(0)
	v_add_f32_e32 v48, v48, v49
	ds_bpermute_b32 v49, v133, v48
	v_cvt_pk_bf16_f32 v51, v54, v55
	v_cvt_pk_bf16_f32 v52, v62, v63
	v_cvt_pk_bf16_f32 v53, v60, v61
	global_store_dwordx4 v[82:83], v[50:53], off offset:256 nt
	s_and_saveexec_b64 s[2:3], s[10:11]
	s_cbranch_execz .LBB0_573
	v_lshlrev_b64 v[50:51], 6, v[80:81]
	v_lshl_add_u64 v[50:51], s[20:21], 0, v[50:51]
	v_lshl_add_u64 v[50:51], s[0:1], 2, v[50:51]
	s_lshl_b32 s88, s44, 2
	v_lshl_add_u64 v[50:51], v[50:51], 0, s[88:89]
	s_waitcnt lgkmcnt(0)
	v_add_f32_e32 v48, v48, v49
	global_store_dword v[50:51], v48, off

; __device__ __forceinline__ u32x4 pack8(const f32x4& a, const f32x4& b) { u32x4 w; w.x = cvt_pk_bf16(a[0], a[1]); w.y = cvt_pk_bf16(a[2], a[3]); w.z = cvt_pk_bf16(b[0], b[1]); w.w = cvt_pk_bf16(b[2], b[3]); return w; }
;     __device__ __forceinline__ void operator()(const f32x4 (&acc)[2][2][4][2], const Unit& u, int ui, int wr, int wc, int fr, int fq) const {
;     ...
;             for (int m = 0; m < 4; ++m) { const int row = row0 + ai * HALF + m * 16; const size_t off = (size_t)row * 1024 + col0; float q = 0.f;
;                 f32x4 v[2][2];
;                 if (basef) {
; #pragma unroll
;                     for (int bj = 0; bj < 2; ++bj) { v[bj][0] = *(const f32x4*)(basef + off + bj * HALF); v[bj][1] = *(const f32x4*)(basef + off + bj * HALF + 4); }
;                 } else {
; #pragma unroll
;                     for (int bj = 0; bj < 2; ++bj) { const u32x4 raw = *(const u32x4*)(xb + off + bj * HALF);
;                         v[bj][0] = (f32x4){__builtin_bit_cast(float, raw.x << 16), __builtin_bit_cast(float, raw.x & 0xffff0000u), __builtin_bit_cast(float, raw.y << 16), __builtin_bit_cast(float, raw.y & 0xffff0000u)};
;                         v[bj][1] = (f32x4){__builtin_bit_cast(float, raw.z << 16), __builtin_bit_cast(float, raw.z & 0xffff0000u), __builtin_bit_cast(float, raw.w << 16), __builtin_bit_cast(float, raw.w & 0xffff0000u)}; }
;                 }
; #pragma unroll
;                 for (int bj = 0; bj < 2; ++bj) {
;                     f32x4 v0 = v[bj][0] + acc[ai][bj][m][0] * alpha, v1 = v[bj][1] + acc[ai][bj][m][1] * alpha;
;                     if (HAS_BIAS) { v0 += bv[bj][0]; v1 += bv[bj][1]; }
;                     if (outf) { *(f32x4*)(outf + off + bj * HALF) = v0; *(f32x4*)(outf + off + bj * HALF + 4) = v1; }
;                     else *(u32x4*)(xb + off + bj * HALF) = pack8(v0, v1);
;                     q += (v0[0] * v0[0] + v0[1] * v0[1]) + (v0[2] * v0[2] + v0[3] * v0[3]) + (v1[0] * v1[0] + v1[1] * v1[1]) + (v1[2] * v1[2] + v1[3] * v1[3]); }
;                 q += __shfl_xor(q, 16); q += __shfl_xor(q, 32);
;                 if (fq == 0) ssp[(size_t)row * 16 + u.pn * 4 + wc] = q;
.LBB0_576:
	s_waitcnt vmcnt(3)
	v_pk_fma_f32 v[44:45], v[44:45], 0.5, v[60:61] op_sel_hi:[1,0,1]
	v_pk_fma_f32 v[46:47], v[46:47], 0.5, v[62:63] op_sel_hi:[1,0,1]
	s_waitcnt vmcnt(2)
	v_pk_fma_f32 v[58:59], v[42:43], 0.5, v[58:59] op_sel_hi:[1,0,1]
	v_pk_fma_f32 v[42:43], v[40:41], 0.5, v[56:57] op_sel_hi:[1,0,1]
	v_cvt_pk_bf16_f32 v40, v44, v45
	v_mul_f32_e32 v44, v44, v44
	v_fmac_f32_e32 v44, v45, v45
	v_mul_f32_e32 v45, v46, v46
	v_fmac_f32_e32 v45, v47, v47
	v_add_f32_e32 v44, v45, v44
	v_mul_f32_e32 v45, v42, v42
	s_waitcnt vmcnt(1)
	v_pk_fma_f32 v[38:39], v[38:39], 0.5, v[54:55] op_sel_hi:[1,0,1]
	v_pk_fma_f32 v[36:37], v[36:37], 0.5, v[52:53] op_sel_hi:[1,0,1]
	v_cvt_pk_bf16_f32 v41, v46, v47
	v_fmac_f32_e32 v45, v43, v43
	s_waitcnt vmcnt(0)
	v_pk_fma_f32 v[46:47], v[32:33], 0.5, v[48:49] op_sel_hi:[1,0,1]
	v_mul_f32_e32 v32, v36, v36
	v_mul_f32_e32 v33, v38, v38
	v_add_f32_e32 v44, v45, v44
	v_mul_f32_e32 v45, v59, v59
	v_fmac_f32_e32 v32, v37, v37
	v_fmac_f32_e32 v33, v39, v39
	v_fmac_f32_e32 v45, v58, v58
	v_add_f32_e32 v32, v33, v32
	v_mul_f32_e32 v33, v46, v46
	v_add_f32_e32 v56, v45, v44
	v_pk_fma_f32 v[44:45], v[34:35], 0.5, v[50:51] op_sel_hi:[1,0,1]
	v_fmac_f32_e32 v33, v47, v47
	v_add_f32_e32 v32, v33, v32
	v_mul_f32_e32 v33, v44, v44
	v_fmac_f32_e32 v33, v45, v45
	v_add_f32_e32 v32, v33, v32
	v_add_f32_e32 v32, v56, v32
	ds_bpermute_b32 v33, v132, v32
	v_cvt_pk_bf16_f32 v42, v42, v43
	v_cvt_pk_bf16_f32 v43, v58, v59
	global_store_dwordx4 v[66:67], v[40:43], off nt
	v_cvt_pk_bf16_f32 v34, v36, v37
	s_waitcnt lgkmcnt(0)
	v_add_f32_e32 v32, v32, v33
	ds_bpermute_b32 v33, v133, v32
	v_cvt_pk_bf16_f32 v35, v38, v39
	v_cvt_pk_bf16_f32 v36, v46, v47
	v_cvt_pk_bf16_f32 v37, v44, v45
	global_store_dwordx4 v[66:67], v[34:37], off offset:256 nt
	s_and_saveexec_b64 s[2:3], s[10:11]
	s_cbranch_execz .LBB0_578
	v_lshlrev_b64 v[34:35], 6, v[64:65]
	v_lshl_add_u64 v[34:35], s[20:21], 0, v[34:35]
	v_lshl_add_u64 v[34:35], s[0:1], 2, v[34:35]
	s_lshl_b32 s88, s44, 2
	v_lshl_add_u64 v[34:35], v[34:35], 0, s[88:89]
	s_waitcnt lgkmcnt(0)
	v_add_f32_e32 v32, v32, v33
	global_store_dword v[34:35], v32, off

; __device__ __forceinline__ u32x4 pack8(const f32x4& a, const f32x4& b) { u32x4 w; w.x = cvt_pk_bf16(a[0], a[1]); w.y = cvt_pk_bf16(a[2], a[3]); w.z = cvt_pk_bf16(b[0], b[1]); w.w = cvt_pk_bf16(b[2], b[3]); return w; }
;     __device__ __forceinline__ void operator()(const f32x4 (&acc)[2][2][4][2], const Unit& u, int ui, int wr, int wc, int fr, int fq) const {
;     ...
;             for (int m = 0; m < 4; ++m) { const int row = row0 + ai * HALF + m * 16; const size_t off = (size_t)row * 1024 + col0; float q = 0.f;
;                 f32x4 v[2][2];
;                 if (basef) {
; #pragma unroll
;                     for (int bj = 0; bj < 2; ++bj) { v[bj][0] = *(const f32x4*)(basef + off + bj * HALF); v[bj][1] = *(const f32x4*)(basef + off + bj * HALF + 4); }
;                 } else {
; #pragma unroll
;                     for (int bj = 0; bj < 2; ++bj) { const u32x4 raw = *(const u32x4*)(xb + off + bj * HALF);
;                         v[bj][0] = (f32x4){__builtin_bit_cast(float, raw.x << 16), __builtin_bit_cast(float, raw.x & 0xffff0000u), __builtin_bit_cast(float, raw.y << 16), __builtin_bit_cast(float, raw.y & 0xffff0000u)};
;                         v[bj][1] = (f32x4){__builtin_bit_cast(float, raw.z << 16), __builtin_bit_cast(float, raw.z & 0xffff0000u), __builtin_bit_cast(float, raw.w << 16), __builtin_bit_cast(float, raw.w & 0xffff0000u)}; }
;                 }
; #pragma unroll
;                 for (int bj = 0; bj < 2; ++bj) {
;                     f32x4 v0 = v[bj][0] + acc[ai][bj][m][0] * alpha, v1 = v[bj][1] + acc[ai][bj][m][1] * alpha;
;                     if (HAS_BIAS) { v0 += bv[bj][0]; v1 += bv[bj][1]; }
;                     if (outf) { *(f32x4*)(outf + off + bj * HALF) = v0; *(f32x4*)(outf + off + bj * HALF + 4) = v1; }
;                     else *(u32x4*)(xb + off + bj * HALF) = pack8(v0, v1);
;                     q += (v0[0] * v0[0] + v0[1] * v0[1]) + (v0[2] * v0[2] + v0[3] * v0[3]) + (v1[0] * v1[0] + v1[1] * v1[1]) + (v1[2] * v1[2] + v1[3] * v1[3]); }
;                 q += __shfl_xor(q, 16); q += __shfl_xor(q, 32);
;                 if (fq == 0) ssp[(size_t)row * 16 + u.pn * 4 + wc] = q;
.LBB0_581:
	s_waitcnt vmcnt(3)
	v_pk_fma_f32 v[28:29], v[28:29], 0.5, v[44:45] op_sel_hi:[1,0,1]
	v_pk_fma_f32 v[30:31], v[30:31], 0.5, v[46:47] op_sel_hi:[1,0,1]
	s_waitcnt vmcnt(2)
	v_pk_fma_f32 v[42:43], v[26:27], 0.5, v[42:43] op_sel_hi:[1,0,1]
	v_pk_fma_f32 v[26:27], v[24:25], 0.5, v[40:41] op_sel_hi:[1,0,1]
	v_cvt_pk_bf16_f32 v24, v28, v29
	v_mul_f32_e32 v28, v28, v28
	v_fmac_f32_e32 v28, v29, v29
	v_mul_f32_e32 v29, v30, v30
	v_fmac_f32_e32 v29, v31, v31
	v_add_f32_e32 v28, v29, v28
	v_mul_f32_e32 v29, v26, v26
	s_waitcnt vmcnt(1)
	v_pk_fma_f32 v[22:23], v[22:23], 0.5, v[38:39] op_sel_hi:[1,0,1]
	v_pk_fma_f32 v[20:21], v[20:21], 0.5, v[36:37] op_sel_hi:[1,0,1]
	v_cvt_pk_bf16_f32 v25, v30, v31
	v_fmac_f32_e32 v29, v27, v27
	s_waitcnt vmcnt(0)
	v_pk_fma_f32 v[30:31], v[16:17], 0.5, v[32:33] op_sel_hi:[1,0,1]
	v_mul_f32_e32 v16, v20, v20
	v_mul_f32_e32 v17, v22, v22
	v_add_f32_e32 v28, v29, v28
	v_mul_f32_e32 v29, v43, v43
	v_fmac_f32_e32 v16, v21, v21
	v_fmac_f32_e32 v17, v23, v23
	v_fmac_f32_e32 v29, v42, v42
	v_add_f32_e32 v16, v17, v16
	v_mul_f32_e32 v17, v30, v30
	v_add_f32_e32 v40, v29, v28
	v_pk_fma_f32 v[28:29], v[18:19], 0.5, v[34:35] op_sel_hi:[1,0,1]
	v_fmac_f32_e32 v17, v31, v31
	v_add_f32_e32 v16, v17, v16
	v_mul_f32_e32 v17, v28, v28
	v_fmac_f32_e32 v17, v29, v29
	v_add_f32_e32 v16, v17, v16
	v_add_f32_e32 v16, v40, v16
	ds_bpermute_b32 v17, v132, v16
	v_cvt_pk_bf16_f32 v26, v26, v27
	v_cvt_pk_bf16_f32 v27, v42, v43
	global_store_dwordx4 v[50:51], v[24:27], off nt
	v_cvt_pk_bf16_f32 v18, v20, v21
	s_waitcnt lgkmcnt(0)
	v_add_f32_e32 v16, v16, v17
	ds_bpermute_b32 v17, v133, v16
	v_cvt_pk_bf16_f32 v19, v22, v23
	v_cvt_pk_bf16_f32 v20, v30, v31
	v_cvt_pk_bf16_f32 v21, v28, v29
	global_store_dwordx4 v[50:51], v[18:21], off offset:256 nt
	s_and_saveexec_b64 s[2:3], s[10:11]
	s_cbranch_execz .LBB0_583
	v_lshlrev_b64 v[18:19], 6, v[48:49]
	v_lshl_add_u64 v[18:19], s[20:21], 0, v[18:19]
	v_lshl_add_u64 v[18:19], s[0:1], 2, v[18:19]
	s_lshl_b32 s88, s44, 2
	v_lshl_add_u64 v[18:19], v[18:19], 0, s[88:89]
	s_waitcnt lgkmcnt(0)
	v_add_f32_e32 v16, v16, v17
	global_store_dword v[18:19], v16, off

; __device__ __forceinline__ u32x4 pack8(const f32x4& a, const f32x4& b) { u32x4 w; w.x = cvt_pk_bf16(a[0], a[1]); w.y = cvt_pk_bf16(a[2], a[3]); w.z = cvt_pk_bf16(b[0], b[1]); w.w = cvt_pk_bf16(b[2], b[3]); return w; }
;     __device__ __forceinline__ void operator()(const f32x4 (&acc)[2][2][4][2], const Unit& u, int ui, int wr, int wc, int fr, int fq) const {
;     ...
;             for (int m = 0; m < 4; ++m) { const int row = row0 + ai * HALF + m * 16; const size_t off = (size_t)row * 1024 + col0; float q = 0.f;
;                 f32x4 v[2][2];
;                 if (basef) {
; #pragma unroll
;                     for (int bj = 0; bj < 2; ++bj) { v[bj][0] = *(const f32x4*)(basef + off + bj * HALF); v[bj][1] = *(const f32x4*)(basef + off + bj * HALF + 4); }
;                 } else {
; #pragma unroll
;                     for (int bj = 0; bj < 2; ++bj) { const u32x4 raw = *(const u32x4*)(xb + off + bj * HALF);
;                         v[bj][0] = (f32x4){__builtin_bit_cast(float, raw.x << 16), __builtin_bit_cast(float, raw.x & 0xffff0000u), __builtin_bit_cast(float, raw.y << 16), __builtin_bit_cast(float, raw.y & 0xffff0000u)};
;                         v[bj][1] = (f32x4){__builtin_bit_cast(float, raw.z << 16), __builtin_bit_cast(float, raw.z & 0xffff0000u), __builtin_bit_cast(float, raw.w << 16), __builtin_bit_cast(float, raw.w & 0xffff0000u)}; }
;                 }
; #pragma unroll
;                 for (int bj = 0; bj < 2; ++bj) {
;                     f32x4 v0 = v[bj][0] + acc[ai][bj][m][0] * alpha, v1 = v[bj][1] + acc[ai][bj][m][1] * alpha;
;                     if (HAS_BIAS) { v0 += bv[bj][0]; v1 += bv[bj][1]; }
;                     if (outf) { *(f32x4*)(outf + off + bj * HALF) = v0; *(f32x4*)(outf + off + bj * HALF + 4) = v1; }
;                     else *(u32x4*)(xb + off + bj * HALF) = pack8(v0, v1);
;                     q += (v0[0] * v0[0] + v0[1] * v0[1]) + (v0[2] * v0[2] + v0[3] * v0[3]) + (v1[0] * v1[0] + v1[1] * v1[1]) + (v1[2] * v1[2] + v1[3] * v1[3]); }
;                 q += __shfl_xor(q, 16); q += __shfl_xor(q, 32);
;                 if (fq == 0) ssp[(size_t)row * 16 + u.pn * 4 + wc] = q;
.LBB0_586:
	s_waitcnt vmcnt(3)
	v_pk_fma_f32 v[12:13], v[12:13], 0.5, v[28:29] op_sel_hi:[1,0,1]
	v_pk_fma_f32 v[14:15], v[14:15], 0.5, v[30:31] op_sel_hi:[1,0,1]
	s_waitcnt vmcnt(2)
	v_pk_fma_f32 v[26:27], v[10:11], 0.5, v[26:27] op_sel_hi:[1,0,1]
	v_pk_fma_f32 v[10:11], v[8:9], 0.5, v[24:25] op_sel_hi:[1,0,1]
	v_cvt_pk_bf16_f32 v8, v12, v13
	v_mul_f32_e32 v12, v12, v12
	v_fmac_f32_e32 v12, v13, v13
	v_mul_f32_e32 v13, v14, v14
	v_fmac_f32_e32 v13, v15, v15
	v_add_f32_e32 v12, v13, v12
	v_mul_f32_e32 v13, v10, v10
	s_waitcnt vmcnt(1)
	v_pk_fma_f32 v[6:7], v[6:7], 0.5, v[22:23] op_sel_hi:[1,0,1]
	v_pk_fma_f32 v[4:5], v[4:5], 0.5, v[20:21] op_sel_hi:[1,0,1]
	v_cvt_pk_bf16_f32 v9, v14, v15
	v_fmac_f32_e32 v13, v11, v11
	s_waitcnt vmcnt(0)
	v_pk_fma_f32 v[14:15], v[0:1], 0.5, v[16:17] op_sel_hi:[1,0,1]
	v_mul_f32_e32 v0, v4, v4
	v_mul_f32_e32 v1, v6, v6
	v_add_f32_e32 v12, v13, v12
	v_mul_f32_e32 v13, v27, v27
	v_fmac_f32_e32 v0, v5, v5
	v_fmac_f32_e32 v1, v7, v7
	v_fmac_f32_e32 v13, v26, v26
	v_add_f32_e32 v0, v1, v0
	v_mul_f32_e32 v1, v14, v14
	v_add_f32_e32 v24, v13, v12
	v_pk_fma_f32 v[12:13], v[2:3], 0.5, v[18:19] op_sel_hi:[1,0,1]
	v_fmac_f32_e32 v1, v15, v15
	v_add_f32_e32 v0, v1, v0
	v_mul_f32_e32 v1, v12, v12
	v_fmac_f32_e32 v1, v13, v13
	v_add_f32_e32 v0, v1, v0
	v_add_f32_e32 v0, v24, v0
	ds_bpermute_b32 v1, v132, v0
	v_cvt_pk_bf16_f32 v10, v10, v11
	v_cvt_pk_bf16_f32 v11, v26, v27
	global_store_dwordx4 v[34:35], v[8:11], off nt
	v_cvt_pk_bf16_f32 v2, v4, v5
	s_waitcnt lgkmcnt(0)
	v_add_f32_e32 v0, v0, v1
	ds_bpermute_b32 v1, v133, v0
	v_cvt_pk_bf16_f32 v3, v6, v7
	v_cvt_pk_bf16_f32 v4, v14, v15
	v_cvt_pk_bf16_f32 v5, v12, v13
	global_store_dwordx4 v[34:35], v[2:5], off offset:256 nt
	s_and_saveexec_b64 s[2:3], s[10:11]
	s_cbranch_execz .LBB0_588
	v_lshlrev_b64 v[2:3], 6, v[32:33]
	v_lshl_add_u64 v[2:3], s[20:21], 0, v[2:3]
	v_lshl_add_u64 v[2:3], s[0:1], 2, v[2:3]
	s_lshl_b32 s88, s44, 2
	v_lshl_add_u64 v[2:3], v[2:3], 0, s[88:89]
	s_waitcnt lgkmcnt(0)
	v_add_f32_e32 v0, v0, v1
	global_store_dword v[2:3], v0, off
